# speedup vs baseline: 1.0081x; 1.0038x over previous
; __device__ __forceinline__ int crow(int r, int hi) { return (r & 3) + 8 * (r >> 2) + 4 * hi; }
; __device__ __forceinline__ void attn_stream(const u16* __restrict__ Qb, const u16* __restrict__ Kh, const u16* __restrict__ Vh,
;                                             int seq, char* lds, f32x16 (&o)[4]) {
;     ...
;   if (hi == 0) li_l[r32] = l_reg;
;   asm volatile("s_waitcnt lgkmcnt(0)" ::: "memory");
; #pragma unroll
;   for (int r = 0; r < 16; ++r) { const float rl = __builtin_amdgcn_rcpf(li_l[crow(r, hi)]);
; #pragma unroll
;     for (int d0 = 0; d0 < 4; ++d0) o[d0][r] *= rl; }
; __device__ __forceinline__ void phase3(const Params& p, char* shm) {
;     ...
;     { const f32x4* o1p = reinterpret_cast<const f32x4*>(o1s + tid * 64);
; #pragma unroll
;       for (int d0 = 0; d0 < 4; ++d0)
; #pragma unroll
;         for (int q = 0; q < 4; ++q) { const f32x4 v1 = o1p[d0 * 4 + q];
; #pragma unroll
;           for (int e = 0; e < 4; ++e) o[d0][q * 4 + e] = v1[e] - lam * o[d0][q * 4 + e]; } }
;     float sw[4];
; #pragma unroll
;     for (int d0 = 0; d0 < 4; ++d0) sw[d0] = p.subln[d0 * 32 + r32] * 0.8f;
;     char* const otb = shm + ((wid * 32 + 4 * hi) * OT_LD + r32) * 2;
; #pragma unroll
;     for (int r = 0; r < 16; ++r) {
;       float ss = 0.f;
; #pragma unroll
;       for (int d0 = 0; d0 < 4; ++d0) ss += o[d0][r] * o[d0][r];
;       ss += __shfl_xor(ss, 1); ss += __shfl_xor(ss, 2); ss += __shfl_xor(ss, 4); ss += __shfl_xor(ss, 8); ss += __shfl_xor(ss, 16);
;       const float rstd = rsqrtf(ss * (1.f / 128.f) + 1e-6f);
.LBB0_401:
	s_or_b64 exec, exec, s[6:7]
	s_and_saveexec_b64 s[0:1], s[4:5]
	ds_write_b32 v212, v192
	s_or_b64 exec, exec, s[0:1]
	s_waitcnt lgkmcnt(0)
	v_add_u32_e32 v66, v204, v190
	v_mov_b32_e32 v131, v1
	ds_read_b128 v[138:141], v66
	s_waitcnt vmcnt(2)
	ds_read_b128 v[144:147], v66 offset:32
	s_waitcnt vmcnt(1)
	ds_read_b128 v[148:151], v66 offset:64
	ds_read_b128 v[152:155], v66 offset:96
	s_waitcnt lgkmcnt(0)
	s_barrier
	v_mov_b32_e32 v156, v2
	v_lshrrev_b32_e32 v252, 6, v131
	v_and_b32_e32 v253, 63, v131
	v_lshlrev_b32_e32 v252, 14, v252
	v_lshl_add_u32 v252, v253, 4, v252
	v_add_u32_e32 v253, 0x1000, v252
	v_add_u32_e32 v254, 0x2000, v252
	v_add_u32_e32 v255, 0x3000, v252
	global_load_dwordx4 v[118:121], v252, s[16:17]
	global_load_dwordx4 v[126:129], v253, s[16:17]
	global_load_dwordx4 v[114:117], v254, s[16:17]
	global_load_dwordx4 v[122:125], v255, s[16:17]
	global_load_dwordx4 v[110:113], v252, s[16:17] offset:1024
	global_load_dwordx4 v[106:109], v253, s[16:17] offset:1024
	global_load_dwordx4 v[102:105], v254, s[16:17] offset:1024
	global_load_dwordx4 v[98:101], v255, s[16:17] offset:1024
	v_and_b32_e32 v143, 31, v131
	v_lshlrev_b32_e32 v68, 2, v143
	global_load_dword v161, v68, s[14:15]
	global_load_dword v163, v68, s[14:15] offset:128
	v_and_b32_e32 v67, 64, v203
	v_xor_b32_e32 v66, 1, v203
	v_add_u32_e32 v2, 64, v67
	v_xor_b32_e32 v69, 2, v203
	v_cmp_lt_i32_e32 vcc, v66, v2
	v_xor_b32_e32 v70, 4, v203
	s_waitcnt vmcnt(10)
	v_mov_b32_e32 v159, v18
	v_mov_b32_e32 v18, v35
	v_cndmask_b32_e32 v35, v203, v66, vcc
	v_cmp_lt_i32_e32 vcc, v69, v2
	global_load_dword v165, v68, s[14:15] offset:256
	global_load_dword v168, v68, s[14:15] offset:384
	v_xor_b32_e32 v68, 8, v203
	v_cndmask_b32_e32 v66, v203, v69, vcc
	v_cmp_lt_i32_e32 vcc, v70, v2
	v_xor_b32_e32 v71, 16, v203
	v_mov_b32_e32 v157, v50
	v_cndmask_b32_e32 v67, v203, v70, vcc
	v_cmp_lt_i32_e32 vcc, v68, v2
	v_mov_b32_e32 v50, v3
	v_lshrrev_b32_e32 v3, 3, v131
	v_cndmask_b32_e32 v68, v203, v68, vcc
	v_cmp_lt_i32_e32 vcc, v71, v2
	v_mov_b32_e32 v158, v34
	v_lshrrev_b32_e32 v34, 1, v131
	v_cndmask_b32_e32 v2, v203, v71, vcc
	v_and_b32_e32 v69, 4, v3
	v_lshlrev_b32_e32 v3, 2, v2
	v_and_or_b32 v2, v34, s69, v69
	v_mul_lo_u32 v169, v2, s70
	v_rcp_f32_e32 v2, v138
	v_rcp_f32_e32 v162, v140
	v_rcp_f32_e32 v140, v146
	v_rcp_f32_e32 v138, v147
	v_pk_mul_f32 v[146:147], v[156:157], v[2:3] op_sel_hi:[1,0]
	v_pk_mul_f32 v[156:157], v[158:159], v[2:3] op_sel_hi:[1,0]
	v_lshlrev_b32_e32 v137, 2, v35
	v_lshlrev_b32_e32 v135, 2, v66
	v_lshlrev_b32_e32 v133, 2, v67
	v_lshlrev_b32_e32 v35, 2, v68
	v_rcp_f32_e32 v164, v141
	v_rcp_f32_e32 v160, v139
	v_or_b32_e32 v139, v169, v143
	v_rcp_f32_e32 v136, v148
	v_rcp_f32_e32 v134, v149
	v_rcp_f32_e32 v132, v150
	v_rcp_f32_e32 v130, v151
	global_load_dwordx4 v[74:77], v252, s[16:17] offset:3072
	global_load_dwordx4 v[90:93], v252, s[16:17] offset:2048
	global_load_dwordx4 v[78:81], v253, s[16:17] offset:3072
	global_load_dwordx4 v[94:97], v253, s[16:17] offset:2048
	global_load_dwordx4 v[66:69], v254, s[16:17] offset:3072
	global_load_dwordx4 v[82:85], v254, s[16:17] offset:2048
	global_load_dwordx4 v[70:73], v255, s[16:17] offset:3072
	s_nop 0
	global_load_dwordx4 v[86:89], v255, s[16:17] offset:2048
	v_rcp_f32_e32 v144, v144
	v_rcp_f32_e32 v142, v145
	s_waitcnt vmcnt(19)
	v_mov_b32_e32 v158, v118
	s_waitcnt vmcnt(18)
	v_mov_b32_e32 v159, v126
	s_waitcnt vmcnt(17)
	v_mov_b32_e32 v166, v114
	s_waitcnt vmcnt(16)
	v_mov_b32_e32 v167, v122
	v_pk_fma_f32 v[146:147], v[188:189], v[146:147], v[158:159] neg_lo:[1,0,0] neg_hi:[1,0,0]
	v_pk_fma_f32 v[156:157], v[188:189], v[156:157], v[166:167] neg_lo:[1,0,0] neg_hi:[1,0,0]
	v_pk_mul_f32 v[158:159], v[146:147], v[146:147]
	v_pk_mul_f32 v[166:167], v[156:157], v[156:157]
	v_add_f32_e32 v2, v158, v159
	v_add_f32_e32 v2, v2, v166
	v_add_f32_e32 v2, v2, v167
	s_nop 1
	v_mov_b32_dpp v34, v2 quad_perm:[1,0,3,2] row_mask:0xf bank_mask:0xf
	s_waitcnt vmcnt(11)
	v_pk_mul_f32 v[148:149], v[50:51], v[160:161] op_sel_hi:[1,0]
	v_pk_mul_f32 v[150:151], v[18:19], v[160:161] op_sel_hi:[1,0]
	v_mul_f32_e32 v51, 0x3f4ccccd, v161
	v_rcp_f32_e32 v118, v152
	s_waitcnt lgkmcnt(0)
	v_add_f32_e32 v122, v2, v34
	s_nop 1
	v_mov_b32_dpp v126, v122 quad_perm:[2,3,0,1] row_mask:0xf bank_mask:0xf
	v_rcp_f32_e32 v114, v153
	v_mov_b32_e32 v152, v116
	v_mov_b32_e32 v153, v124
	s_waitcnt vmcnt(10)
	v_mul_f32_e32 v50, 0x3f4ccccd, v163
	s_waitcnt lgkmcnt(0)
	v_add_f32_e32 v122, v122, v126
	s_nop 1
	v_mov_b32_dpp v126, v122 row_half_mirror row_mask:0xf bank_mask:0xf
	s_waitcnt vmcnt(9)
	v_mul_f32_e32 v19, 0x3f4ccccd, v165
	s_waitcnt vmcnt(8)
	v_mul_f32_e32 v18, 0x3f4ccccd, v168
	v_mov_b32_e32 v124, v117
	v_mov_b32_e32 v117, v22
	s_waitcnt lgkmcnt(0)
	v_add_f32_e32 v141, v122, v126
	s_nop 1
	v_mov_b32_dpp v143, v141 row_mirror row_mask:0xf bank_mask:0xf
	v_mov_b32_e32 v122, v115
	v_mov_b32_e32 v126, v119
	v_pk_fma_f32 v[126:127], v[188:189], v[148:149], v[126:127] neg_lo:[1,0,0] neg_hi:[1,0,0]
	v_pk_fma_f32 v[122:123], v[188:189], v[150:151], v[122:123] neg_lo:[1,0,0] neg_hi:[1,0,0]
	s_waitcnt lgkmcnt(0)
	v_add_f32_e32 v115, v141, v143
	ds_bpermute_b32 v119, v3, v115
	v_pk_mul_f32 v[148:149], v[126:127], v[126:127]
	v_pk_mul_f32 v[150:151], v[122:123], v[122:123]
	v_rcp_f32_e32 v34, v154
	v_rcp_f32_e32 v2, v155
	s_waitcnt lgkmcnt(0)
	v_add_f32_e32 v115, v115, v119
	v_add_f32_e32 v119, v148, v149
	v_add_f32_e32 v119, v119, v150
	v_add_f32_e32 v119, v119, v151
	v_fmamk_f32 v115, v115, 0x3c000000, v187
	s_nop 1
	v_mov_b32_dpp v141, v119 quad_perm:[1,0,3,2] row_mask:0xf bank_mask:0xf
	v_mul_f32_e32 v143, 0x4b800000, v115
	v_cmp_gt_f32_e32 vcc, s71, v115
	v_mov_b32_e32 v148, v120
	v_mov_b32_e32 v149, v128
	v_cndmask_b32_e32 v115, v115, v143, vcc
	v_rsq_f32_e32 v143, v115
	s_waitcnt lgkmcnt(0)
; __device__ __forceinline__ u16 f2bf(float f) { return (u16)(cvtpk(f, f) & 0xffffu); }
; __device__ __forceinline__ void phase3(const Params& p, char* shm) {
;     ...
;     for (int r = 0; r < 16; ++r) {
;       float ss = 0.f;
; #pragma unroll
;       for (int d0 = 0; d0 < 4; ++d0) ss += o[d0][r] * o[d0][r];
;       ss += __shfl_xor(ss, 1); ss += __shfl_xor(ss, 2); ss += __shfl_xor(ss, 4); ss += __shfl_xor(ss, 8); ss += __shfl_xor(ss, 16);
;       const float rstd = rsqrtf(ss * (1.f / 128.f) + 1e-6f);
; #pragma unroll
;       for (int d0 = 0; d0 < 4; ++d0) *(u16*)(otb + (((r & 3) + 8 * (r >> 2)) * OT_LD + d0 * 32) * 2) = f2bf(o[d0][r] * rstd * sw[d0]);
;     }
	v_add_f32_e32 v119, v119, v141
	s_nop 1
	v_mov_b32_dpp v141, v119 quad_perm:[2,3,0,1] row_mask:0xf bank_mask:0xf
	v_lshl_add_u32 v115, v139, 1, 0
	v_mul_f32_e32 v139, 0x45800000, v143
	v_cndmask_b32_e32 v139, v143, v139, vcc
	v_mul_f32_e32 v143, v146, v139
	v_mul_f32_e32 v143, v51, v143
	s_waitcnt lgkmcnt(0)
	v_add_f32_e32 v119, v119, v141
	s_nop 0
	v_cvt_pk_bf16_f32 v143, v143, v143
	s_nop 1
	v_mov_b32_dpp v141, v119 row_half_mirror row_mask:0xf bank_mask:0xf
	ds_write_b16 v115, v143
	v_mul_f32_e32 v143, v147, v139
	v_mov_b32_e32 v146, v4
	v_mov_b32_e32 v147, v52
	v_pk_mul_f32 v[146:147], v[146:147], v[162:163] op_sel_hi:[1,0]
	v_mov_b32_e32 v150, v36
	v_mov_b32_e32 v151, v20
	v_pk_fma_f32 v[146:147], v[188:189], v[146:147], v[148:149] neg_lo:[1,0,0] neg_hi:[1,0,0]
	v_pk_mul_f32 v[150:151], v[150:151], v[162:163] op_sel_hi:[1,0]
	v_pk_mul_f32 v[148:149], v[146:147], v[146:147]
	v_pk_fma_f32 v[150:151], v[188:189], v[150:151], v[152:153] neg_lo:[1,0,0] neg_hi:[1,0,0]
	v_add_f32_e32 v4, v148, v149
	v_pk_mul_f32 v[152:153], v[150:151], v[150:151]
	s_waitcnt lgkmcnt(1)
	v_add_f32_e32 v119, v119, v141
	v_add_f32_e32 v4, v4, v152
	s_nop 1
	v_mov_b32_dpp v141, v119 row_mirror row_mask:0xf bank_mask:0xf
	v_add_f32_e32 v4, v4, v153
	s_nop 1
	v_mov_b32_dpp v20, v4 quad_perm:[1,0,3,2] row_mask:0xf bank_mask:0xf
	v_mul_f32_e32 v143, v50, v143
	s_nop 0
	v_cvt_pk_bf16_f32 v143, v143, v143
	s_waitcnt lgkmcnt(0)
	v_add_f32_e32 v119, v119, v141
	ds_bpermute_b32 v141, v3, v119
	s_waitcnt lgkmcnt(1)
	v_add_f32_e32 v4, v4, v20
	s_nop 1
	v_mov_b32_dpp v20, v4 quad_perm:[2,3,0,1] row_mask:0xf bank_mask:0xf
	ds_write_b16 v115, v143 offset:64
	v_mul_f32_e32 v143, v156, v139
	s_waitcnt lgkmcnt(1)
	v_add_f32_e32 v119, v119, v141
	v_fmamk_f32 v119, v119, 0x3c000000, v187
	s_waitcnt lgkmcnt(1)
	v_add_f32_e32 v4, v4, v20
	v_mul_f32_e32 v141, 0x4b800000, v119
	v_cmp_gt_f32_e32 vcc, s71, v119
	s_nop 1
	v_mov_b32_dpp v20, v4 row_half_mirror row_mask:0xf bank_mask:0xf
	v_mul_f32_e32 v139, v157, v139
	v_cndmask_b32_e32 v119, v119, v141, vcc
	v_rsq_f32_e32 v119, v119
	v_mul_f32_e32 v143, v19, v143
	v_mul_f32_e32 v36, v18, v139
	s_nop 0
	v_cvt_pk_bf16_f32 v143, v143, v143
	ds_write_b16 v115, v143 offset:128
	s_nop 0
	v_cvt_pk_bf16_f32 v36, v36, v36
	s_waitcnt lgkmcnt(1)
	v_add_f32_e32 v4, v4, v20
	ds_write_b16 v115, v36 offset:192
	v_mul_f32_e32 v36, 0x45800000, v119
	s_nop 1
	v_mov_b32_dpp v20, v4 row_mirror row_mask:0xf bank_mask:0xf
	v_cndmask_b32_e32 v36, v119, v36, vcc
	v_mul_f32_e32 v52, v126, v36
	v_mul_f32_e32 v52, v51, v52
	s_nop 0
	v_cvt_pk_bf16_f32 v52, v52, v52
	ds_write_b16 v115, v52 offset:272
	v_mul_f32_e32 v52, v127, v36
	s_waitcnt lgkmcnt(1)
	v_add_f32_e32 v4, v4, v20
	v_mul_f32_e32 v52, v50, v52
	ds_bpermute_b32 v20, v3, v4
	s_nop 0
	v_cvt_pk_bf16_f32 v52, v52, v52
	ds_write_b16 v115, v52 offset:336
	v_mul_f32_e32 v52, v122, v36
	v_mul_f32_e32 v52, v19, v52
	s_nop 0
	v_cvt_pk_bf16_f32 v52, v52, v52
	ds_write_b16 v115, v52 offset:400
	s_waitcnt lgkmcnt(2)
	v_add_f32_e32 v4, v4, v20
	v_mov_b32_e32 v52, v5
	v_fmamk_f32 v119, v4, 0x3c000000, v187
	v_pk_mul_f32 v[4:5], v[52:53], v[164:165] op_sel_hi:[1,0]
	v_mov_b32_e32 v128, v121
	v_mov_b32_e32 v20, v37
	v_mul_f32_e32 v36, v123, v36
	v_pk_fma_f32 v[4:5], v[188:189], v[4:5], v[128:129] neg_lo:[1,0,0] neg_hi:[1,0,0]
	v_pk_mul_f32 v[20:21], v[20:21], v[164:165] op_sel_hi:[1,0]
	v_mul_f32_e32 v36, v18, v36
	v_pk_mul_f32 v[52:53], v[4:5], v[4:5]
	v_pk_fma_f32 v[20:21], v[188:189], v[20:21], v[124:125] neg_lo:[1,0,0] neg_hi:[1,0,0]
	s_nop 0
	v_cvt_pk_bf16_f32 v116, v36, v36
	v_add_f32_e32 v52, v52, v53
	v_pk_mul_f32 v[36:37], v[20:21], v[20:21]
	v_cmp_gt_f32_e32 vcc, s71, v119
	v_add_f32_e32 v36, v52, v36
	v_add_f32_e32 v36, v36, v37
	s_nop 1
	v_mov_b32_dpp v37, v36 quad_perm:[1,0,3,2] row_mask:0xf bank_mask:0xf
	v_mul_f32_e32 v52, 0x4b800000, v119
	v_cndmask_b32_e32 v52, v119, v52, vcc
	v_rsq_f32_e32 v52, v52
	ds_write_b16 v115, v116 offset:464
	s_waitcnt lgkmcnt(1)
	v_add_f32_e32 v36, v36, v37
	s_nop 1
	v_mov_b32_dpp v37, v36 quad_perm:[2,3,0,1] row_mask:0xf bank_mask:0xf
	v_mul_f32_e32 v53, 0x45800000, v52
	v_cndmask_b32_e32 v52, v52, v53, vcc
	v_mul_f32_e32 v53, v146, v52
	v_mul_f32_e32 v53, v51, v53
	s_waitcnt lgkmcnt(0)
	v_add_f32_e32 v36, v36, v37
	s_nop 1
	v_mov_b32_dpp v37, v36 row_half_mirror row_mask:0xf bank_mask:0xf
	s_nop 0
	v_cvt_pk_bf16_f32 v53, v53, v53
	ds_write_b16 v115, v53 offset:544
	v_mul_f32_e32 v53, v147, v52
	v_mul_f32_e32 v53, v50, v53
	s_waitcnt lgkmcnt(1)
	v_add_f32_e32 v36, v36, v37
	s_nop 1
	v_mov_b32_dpp v37, v36 row_mirror row_mask:0xf bank_mask:0xf
	s_nop 0
	v_cvt_pk_bf16_f32 v53, v53, v53
	ds_write_b16 v115, v53 offset:608
	v_mul_f32_e32 v53, v150, v52
	v_mul_f32_e32 v53, v19, v53
	s_waitcnt lgkmcnt(1)
	v_add_f32_e32 v36, v36, v37
	ds_bpermute_b32 v37, v3, v36
	s_nop 0
	v_cvt_pk_bf16_f32 v53, v53, v53
	ds_write_b16 v115, v53 offset:672
	v_mul_f32_e32 v119, v151, v52
	v_mov_b32_e32 v52, v110
	s_waitcnt lgkmcnt(1)
	v_add_f32_e32 v36, v36, v37
	v_fmamk_f32 v36, v36, 0x3c000000, v187
	v_mul_f32_e32 v37, 0x4b800000, v36
	v_cmp_gt_f32_e32 vcc, s71, v36
	v_mov_b32_e32 v53, v106
	v_mov_b32_e32 v116, v38
	v_cndmask_b32_e32 v36, v36, v37, vcc
	v_rsq_f32_e32 v122, v36
	v_mov_b32_e32 v36, v6
	v_mov_b32_e32 v37, v54
	v_pk_mul_f32 v[36:37], v[36:37], v[144:145] op_sel_hi:[1,0]
	v_pk_mul_f32 v[116:117], v[116:117], v[144:145] op_sel_hi:[1,0]
	v_pk_fma_f32 v[36:37], v[188:189], v[36:37], v[52:53] neg_lo:[1,0,0] neg_hi:[1,0,0]
	v_mov_b32_e32 v120, v102
	v_mov_b32_e32 v121, v98
	v_pk_mul_f32 v[52:53], v[36:37], v[36:37]
	v_pk_fma_f32 v[116:117], v[188:189], v[116:117], v[120:121] neg_lo:[1,0,0] neg_hi:[1,0,0]
	v_add_f32_e32 v6, v52, v53
	v_pk_mul_f32 v[120:121], v[116:117], v[116:117]
	v_mul_f32_e32 v38, v18, v119
	v_add_f32_e32 v6, v6, v120
	v_add_f32_e32 v6, v6, v121
	s_nop 1
	v_mov_b32_dpp v22, v6 quad_perm:[1,0,3,2] row_mask:0xf bank_mask:0xf
	s_nop 0
	v_cvt_pk_bf16_f32 v38, v38, v38
	ds_write_b16 v115, v38 offset:736
	v_mul_f32_e32 v38, 0x45800000, v122
	v_cndmask_b32_e32 v38, v122, v38, vcc
	s_waitcnt lgkmcnt(1)
; __device__ __forceinline__ u16 f2bf(float f) { return (u16)(cvtpk(f, f) & 0xffffu); }
; __device__ __forceinline__ void phase3(const Params& p, char* shm) {
;     ...
;     for (int r = 0; r < 16; ++r) {
;       float ss = 0.f;
; #pragma unroll
;       for (int d0 = 0; d0 < 4; ++d0) ss += o[d0][r] * o[d0][r];
;       ss += __shfl_xor(ss, 1); ss += __shfl_xor(ss, 2); ss += __shfl_xor(ss, 4); ss += __shfl_xor(ss, 8); ss += __shfl_xor(ss, 16);
;       const float rstd = rsqrtf(ss * (1.f / 128.f) + 1e-6f);
; #pragma unroll
;       for (int d0 = 0; d0 < 4; ++d0) *(u16*)(otb + (((r & 3) + 8 * (r >> 2)) * OT_LD + d0 * 32) * 2) = f2bf(o[d0][r] * rstd * sw[d0]);
;     }
	v_add_f32_e32 v6, v6, v22
	s_nop 1
	v_mov_b32_dpp v22, v6 quad_perm:[2,3,0,1] row_mask:0xf bank_mask:0xf
	v_mul_f32_e32 v4, v4, v38
	v_mul_f32_e32 v4, v51, v4
	s_nop 0
	v_cvt_pk_bf16_f32 v4, v4, v4
	ds_write_b16 v115, v4 offset:816
	s_waitcnt lgkmcnt(1)
	v_add_f32_e32 v6, v6, v22
	s_nop 1
	v_mov_b32_dpp v22, v6 row_half_mirror row_mask:0xf bank_mask:0xf
	v_mul_f32_e32 v4, v5, v38
	v_mul_f32_e32 v4, v50, v4
	s_nop 0
	v_cvt_pk_bf16_f32 v4, v4, v4
	ds_write_b16 v115, v4 offset:880
	s_waitcnt lgkmcnt(1)
	v_add_f32_e32 v5, v6, v22
	s_nop 1
	v_mov_b32_dpp v6, v5 row_mirror row_mask:0xf bank_mask:0xf
	v_mul_f32_e32 v4, v20, v38
	v_mul_f32_e32 v4, v19, v4
	s_nop 0
	v_cvt_pk_bf16_f32 v4, v4, v4
	ds_write_b16 v115, v4 offset:944
	s_waitcnt lgkmcnt(1)
	v_add_f32_e32 v5, v5, v6
	ds_bpermute_b32 v6, v3, v5
	v_mul_f32_e32 v4, v21, v38
	v_mul_f32_e32 v4, v18, v4
	s_nop 0
	v_cvt_pk_bf16_f32 v38, v4, v4
	v_mov_b32_e32 v54, v7
	s_waitcnt lgkmcnt(0)
	v_add_f32_e32 v4, v5, v6
	v_fmamk_f32 v52, v4, 0x3c000000, v187
	v_pk_mul_f32 v[4:5], v[54:55], v[142:143] op_sel_hi:[1,0]
	v_mov_b32_e32 v106, v111
	v_mov_b32_e32 v22, v39
	v_pk_fma_f32 v[4:5], v[188:189], v[4:5], v[106:107] neg_lo:[1,0,0] neg_hi:[1,0,0]
	v_pk_mul_f32 v[20:21], v[22:23], v[142:143] op_sel_hi:[1,0]
	v_mov_b32_e32 v98, v103
	v_pk_mul_f32 v[6:7], v[4:5], v[4:5]
	v_pk_fma_f32 v[20:21], v[188:189], v[20:21], v[98:99] neg_lo:[1,0,0] neg_hi:[1,0,0]
	v_add_f32_e32 v6, v6, v7
	v_pk_mul_f32 v[22:23], v[20:21], v[20:21]
	v_cmp_gt_f32_e32 vcc, s71, v52
	v_add_f32_e32 v6, v6, v22
	v_add_f32_e32 v6, v6, v23
	s_nop 1
	v_mov_b32_dpp v7, v6 quad_perm:[1,0,3,2] row_mask:0xf bank_mask:0xf
	v_mul_f32_e32 v22, 0x4b800000, v52
	v_cndmask_b32_e32 v22, v52, v22, vcc
	v_rsq_f32_e32 v22, v22
	ds_write_b16 v115, v38 offset:1008
	s_waitcnt lgkmcnt(1)
	v_add_f32_e32 v6, v6, v7
	s_nop 1
	v_mov_b32_dpp v7, v6 quad_perm:[2,3,0,1] row_mask:0xf bank_mask:0xf
	v_mul_f32_e32 v23, 0x45800000, v22
	v_cndmask_b32_e32 v22, v22, v23, vcc
	v_mul_f32_e32 v23, v36, v22
	v_mul_f32_e32 v23, v51, v23
	s_waitcnt lgkmcnt(0)
	v_add_f32_e32 v6, v6, v7
	s_nop 1
	v_mov_b32_dpp v7, v6 row_half_mirror row_mask:0xf bank_mask:0xf
	s_nop 0
	v_cvt_pk_bf16_f32 v23, v23, v23
	ds_write_b16 v115, v23 offset:2176
	v_mul_f32_e32 v23, v37, v22
	v_mul_f32_e32 v23, v50, v23
	s_waitcnt lgkmcnt(1)
	v_add_f32_e32 v6, v6, v7
	s_nop 1
	v_mov_b32_dpp v7, v6 row_mirror row_mask:0xf bank_mask:0xf
	s_nop 0
	v_cvt_pk_bf16_f32 v23, v23, v23
	ds_write_b16 v115, v23 offset:2240
	v_mul_f32_e32 v23, v116, v22
	v_mul_f32_e32 v23, v19, v23
	s_waitcnt lgkmcnt(1)
	v_add_f32_e32 v6, v6, v7
	ds_bpermute_b32 v7, v3, v6
	s_nop 0
	v_cvt_pk_bf16_f32 v23, v23, v23
	ds_write_b16 v115, v23 offset:2304
	v_mul_f32_e32 v52, v117, v22
	v_mov_b32_e32 v22, v112
	s_waitcnt lgkmcnt(1)
	v_add_f32_e32 v6, v6, v7
	v_fmamk_f32 v6, v6, 0x3c000000, v187
	v_mul_f32_e32 v7, 0x4b800000, v6
	v_cmp_gt_f32_e32 vcc, s71, v6
	v_mov_b32_e32 v23, v108
	v_mov_b32_e32 v36, v40
	v_cndmask_b32_e32 v6, v6, v7, vcc
	v_rsq_f32_e32 v53, v6
	v_mov_b32_e32 v6, v8
	v_mov_b32_e32 v7, v56
	v_pk_mul_f32 v[6:7], v[6:7], v[140:141] op_sel_hi:[1,0]
	v_mov_b32_e32 v37, v24
	v_pk_fma_f32 v[6:7], v[188:189], v[6:7], v[22:23] neg_lo:[1,0,0] neg_hi:[1,0,0]
	v_pk_mul_f32 v[36:37], v[36:37], v[140:141] op_sel_hi:[1,0]
	v_mov_b32_e32 v38, v104
	v_mov_b32_e32 v39, v100
	v_pk_mul_f32 v[22:23], v[6:7], v[6:7]
	v_pk_fma_f32 v[36:37], v[188:189], v[36:37], v[38:39] neg_lo:[1,0,0] neg_hi:[1,0,0]
	v_add_f32_e32 v8, v22, v23
	v_pk_mul_f32 v[38:39], v[36:37], v[36:37]
	v_mul_f32_e32 v23, v18, v52
	v_add_f32_e32 v8, v8, v38
	v_add_f32_e32 v8, v8, v39
	s_nop 1
	v_mov_b32_dpp v22, v8 quad_perm:[1,0,3,2] row_mask:0xf bank_mask:0xf
	s_nop 0
	v_cvt_pk_bf16_f32 v23, v23, v23
	ds_write_b16 v115, v23 offset:2368
	v_mul_f32_e32 v23, 0x45800000, v53
	v_cndmask_b32_e32 v23, v53, v23, vcc
	s_waitcnt lgkmcnt(1)
	v_add_f32_e32 v8, v8, v22
	s_nop 1
	v_mov_b32_dpp v22, v8 quad_perm:[2,3,0,1] row_mask:0xf bank_mask:0xf
	v_mul_f32_e32 v4, v4, v23
	v_mul_f32_e32 v4, v51, v4
	s_nop 0
	v_cvt_pk_bf16_f32 v4, v4, v4
	ds_write_b16 v115, v4 offset:2448
	s_waitcnt lgkmcnt(1)
	v_add_f32_e32 v8, v8, v22
	s_nop 1
	v_mov_b32_dpp v22, v8 row_half_mirror row_mask:0xf bank_mask:0xf
	v_mul_f32_e32 v4, v5, v23
	v_mul_f32_e32 v4, v50, v4
	s_nop 0
	v_cvt_pk_bf16_f32 v4, v4, v4
	ds_write_b16 v115, v4 offset:2512
	s_waitcnt lgkmcnt(1)
	v_add_f32_e32 v5, v8, v22
	s_nop 1
	v_mov_b32_dpp v8, v5 row_mirror row_mask:0xf bank_mask:0xf
	v_mul_f32_e32 v4, v20, v23
	v_mul_f32_e32 v4, v19, v4
	s_nop 0
	v_cvt_pk_bf16_f32 v4, v4, v4
	ds_write_b16 v115, v4 offset:2576
	s_waitcnt lgkmcnt(1)
	v_add_f32_e32 v5, v5, v8
	ds_bpermute_b32 v8, v3, v5
	v_mul_f32_e32 v4, v21, v23
	v_mul_f32_e32 v4, v18, v4
	s_nop 0
	v_cvt_pk_bf16_f32 v38, v4, v4
	v_mov_b32_e32 v56, v9
	s_waitcnt lgkmcnt(0)
	v_add_f32_e32 v4, v5, v8
	v_fmamk_f32 v39, v4, 0x3c000000, v187
	v_pk_mul_f32 v[4:5], v[56:57], v[138:139] op_sel_hi:[1,0]
	v_mov_b32_e32 v108, v113
	v_mov_b32_e32 v24, v41
	v_pk_fma_f32 v[4:5], v[188:189], v[4:5], v[108:109] neg_lo:[1,0,0] neg_hi:[1,0,0]
	v_pk_mul_f32 v[20:21], v[24:25], v[138:139] op_sel_hi:[1,0]
	v_mov_b32_e32 v100, v105
	v_pk_mul_f32 v[8:9], v[4:5], v[4:5]
	v_pk_fma_f32 v[20:21], v[188:189], v[20:21], v[100:101] neg_lo:[1,0,0] neg_hi:[1,0,0]
	v_add_f32_e32 v8, v8, v9
	v_pk_mul_f32 v[22:23], v[20:21], v[20:21]
	v_cmp_gt_f32_e32 vcc, s71, v39
	v_add_f32_e32 v8, v8, v22
	v_add_f32_e32 v8, v8, v23
	s_nop 1
	v_mov_b32_dpp v9, v8 quad_perm:[1,0,3,2] row_mask:0xf bank_mask:0xf
	v_mul_f32_e32 v22, 0x4b800000, v39
	v_cndmask_b32_e32 v22, v39, v22, vcc
	v_rsq_f32_e32 v22, v22
	ds_write_b16 v115, v38 offset:2640
	s_waitcnt lgkmcnt(1)
; __device__ __forceinline__ u16 f2bf(float f) { return (u16)(cvtpk(f, f) & 0xffffu); }
; __device__ __forceinline__ void phase3(const Params& p, char* shm) {
;     ...
;     for (int r = 0; r < 16; ++r) {
;       float ss = 0.f;
; #pragma unroll
;       for (int d0 = 0; d0 < 4; ++d0) ss += o[d0][r] * o[d0][r];
;       ss += __shfl_xor(ss, 1); ss += __shfl_xor(ss, 2); ss += __shfl_xor(ss, 4); ss += __shfl_xor(ss, 8); ss += __shfl_xor(ss, 16);
;       const float rstd = rsqrtf(ss * (1.f / 128.f) + 1e-6f);
; #pragma unroll
;       for (int d0 = 0; d0 < 4; ++d0) *(u16*)(otb + (((r & 3) + 8 * (r >> 2)) * OT_LD + d0 * 32) * 2) = f2bf(o[d0][r] * rstd * sw[d0]);
;     }
	v_add_f32_e32 v8, v8, v9
	s_nop 1
	v_mov_b32_dpp v9, v8 quad_perm:[2,3,0,1] row_mask:0xf bank_mask:0xf
	v_mul_f32_e32 v23, 0x45800000, v22
	v_cndmask_b32_e32 v22, v22, v23, vcc
	v_mul_f32_e32 v6, v6, v22
	v_mul_f32_e32 v6, v51, v6
	s_waitcnt lgkmcnt(0)
	v_add_f32_e32 v8, v8, v9
	s_nop 1
	v_mov_b32_dpp v9, v8 row_half_mirror row_mask:0xf bank_mask:0xf
	s_nop 0
	v_cvt_pk_bf16_f32 v6, v6, v6
	ds_write_b16 v115, v6 offset:2720
	v_mul_f32_e32 v6, v7, v22
	v_mul_f32_e32 v6, v50, v6
	s_waitcnt lgkmcnt(1)
	v_add_f32_e32 v7, v8, v9
	s_nop 1
	v_mov_b32_dpp v8, v7 row_mirror row_mask:0xf bank_mask:0xf
	s_nop 0
	v_cvt_pk_bf16_f32 v6, v6, v6
	ds_write_b16 v115, v6 offset:2784
	v_mul_f32_e32 v6, v36, v22
	v_mul_f32_e32 v6, v19, v6
	s_waitcnt lgkmcnt(1)
	v_add_f32_e32 v7, v7, v8
	ds_bpermute_b32 v8, v3, v7
	s_nop 0
	v_cvt_pk_bf16_f32 v6, v6, v6
	ds_write_b16 v115, v6 offset:2848
	v_mul_f32_e32 v36, v37, v22
	s_waitcnt vmcnt(4)
	v_mov_b32_e32 v9, v94
	s_waitcnt lgkmcnt(1)
	v_add_f32_e32 v6, v7, v8
	v_fmamk_f32 v6, v6, 0x3c000000, v187
	v_mul_f32_e32 v7, 0x4b800000, v6
	v_cmp_gt_f32_e32 vcc, s71, v6
	v_mov_b32_e32 v8, v90
	v_mov_b32_e32 v22, v42
	v_cndmask_b32_e32 v6, v6, v7, vcc
	v_rsq_f32_e32 v37, v6
	v_mov_b32_e32 v6, v10
	v_mov_b32_e32 v7, v58
	v_pk_mul_f32 v[6:7], v[6:7], v[136:137] op_sel_hi:[1,0]
	v_mov_b32_e32 v23, v26
	v_pk_fma_f32 v[6:7], v[188:189], v[6:7], v[8:9] neg_lo:[1,0,0] neg_hi:[1,0,0]
	v_pk_mul_f32 v[22:23], v[22:23], v[136:137] op_sel_hi:[1,0]
	s_waitcnt vmcnt(2)
	v_mov_b32_e32 v24, v82
	s_waitcnt vmcnt(0)
	v_mov_b32_e32 v25, v86
	v_pk_mul_f32 v[8:9], v[6:7], v[6:7]
	v_pk_fma_f32 v[22:23], v[188:189], v[22:23], v[24:25] neg_lo:[1,0,0] neg_hi:[1,0,0]
	v_add_f32_e32 v8, v8, v9
	v_pk_mul_f32 v[24:25], v[22:23], v[22:23]
	v_mul_f32_e32 v10, v18, v36
	v_add_f32_e32 v8, v8, v24
	v_add_f32_e32 v8, v8, v25
	s_nop 1
	v_mov_b32_dpp v9, v8 quad_perm:[1,0,3,2] row_mask:0xf bank_mask:0xf
	s_nop 0
	v_cvt_pk_bf16_f32 v10, v10, v10
	ds_write_b16 v115, v10 offset:2912
	v_mul_f32_e32 v10, 0x45800000, v37
	v_cndmask_b32_e32 v10, v37, v10, vcc
	s_waitcnt lgkmcnt(1)
	v_add_f32_e32 v8, v8, v9
	s_nop 1
	v_mov_b32_dpp v9, v8 quad_perm:[2,3,0,1] row_mask:0xf bank_mask:0xf
	v_mul_f32_e32 v4, v4, v10
	v_mul_f32_e32 v4, v51, v4
	s_nop 0
	v_cvt_pk_bf16_f32 v4, v4, v4
	ds_write_b16 v115, v4 offset:2992
	s_waitcnt lgkmcnt(1)
	v_add_f32_e32 v8, v8, v9
	s_nop 1
	v_mov_b32_dpp v9, v8 row_half_mirror row_mask:0xf bank_mask:0xf
	v_mul_f32_e32 v4, v5, v10
	v_mul_f32_e32 v4, v50, v4
	s_nop 0
	v_cvt_pk_bf16_f32 v4, v4, v4
	ds_write_b16 v115, v4 offset:3056
	s_waitcnt lgkmcnt(1)
	v_add_f32_e32 v5, v8, v9
	s_nop 1
	v_mov_b32_dpp v8, v5 row_mirror row_mask:0xf bank_mask:0xf
	v_mul_f32_e32 v4, v20, v10
	v_mul_f32_e32 v4, v19, v4
	s_nop 0
	v_cvt_pk_bf16_f32 v4, v4, v4
	ds_write_b16 v115, v4 offset:3120
	s_waitcnt lgkmcnt(1)
	v_add_f32_e32 v5, v5, v8
	ds_bpermute_b32 v8, v3, v5
	v_mul_f32_e32 v4, v21, v10
	v_mul_f32_e32 v4, v18, v4
	s_nop 0
	v_cvt_pk_bf16_f32 v24, v4, v4
	v_mov_b32_e32 v58, v11
	s_waitcnt lgkmcnt(0)
	v_add_f32_e32 v4, v5, v8
	v_fmamk_f32 v25, v4, 0x3c000000, v187
	v_pk_mul_f32 v[4:5], v[58:59], v[134:135] op_sel_hi:[1,0]
	v_mov_b32_e32 v94, v91
	v_mov_b32_e32 v26, v43
	v_pk_fma_f32 v[4:5], v[188:189], v[4:5], v[94:95] neg_lo:[1,0,0] neg_hi:[1,0,0]
	v_pk_mul_f32 v[10:11], v[26:27], v[134:135] op_sel_hi:[1,0]
	v_mov_b32_e32 v86, v83
	v_pk_mul_f32 v[8:9], v[4:5], v[4:5]
	v_pk_fma_f32 v[10:11], v[188:189], v[10:11], v[86:87] neg_lo:[1,0,0] neg_hi:[1,0,0]
	v_add_f32_e32 v8, v8, v9
	v_pk_mul_f32 v[20:21], v[10:11], v[10:11]
	v_cmp_gt_f32_e32 vcc, s71, v25
	v_add_f32_e32 v8, v8, v20
	v_add_f32_e32 v8, v8, v21
	s_nop 1
	v_mov_b32_dpp v9, v8 quad_perm:[1,0,3,2] row_mask:0xf bank_mask:0xf
	v_mul_f32_e32 v20, 0x4b800000, v25
	v_cndmask_b32_e32 v20, v25, v20, vcc
	v_rsq_f32_e32 v20, v20
	ds_write_b16 v115, v24 offset:3184
	s_waitcnt lgkmcnt(1)
	v_add_f32_e32 v8, v8, v9
	s_nop 1
	v_mov_b32_dpp v9, v8 quad_perm:[2,3,0,1] row_mask:0xf bank_mask:0xf
	v_mul_f32_e32 v21, 0x45800000, v20
	v_cndmask_b32_e32 v20, v20, v21, vcc
	v_mul_f32_e32 v6, v6, v20
	v_mul_f32_e32 v6, v51, v6
	s_waitcnt lgkmcnt(0)
	v_add_f32_e32 v8, v8, v9
	s_nop 1
	v_mov_b32_dpp v9, v8 row_half_mirror row_mask:0xf bank_mask:0xf
	s_nop 0
	v_cvt_pk_bf16_f32 v6, v6, v6
	ds_write_b16 v115, v6 offset:4352
	v_mul_f32_e32 v6, v7, v20
	v_mul_f32_e32 v6, v50, v6
	s_waitcnt lgkmcnt(1)
	v_add_f32_e32 v7, v8, v9
	s_nop 1
	v_mov_b32_dpp v8, v7 row_mirror row_mask:0xf bank_mask:0xf
	s_nop 0
	v_cvt_pk_bf16_f32 v6, v6, v6
	ds_write_b16 v115, v6 offset:4416
	v_mul_f32_e32 v6, v22, v20
	v_mul_f32_e32 v6, v19, v6
	s_waitcnt lgkmcnt(1)
	v_add_f32_e32 v7, v7, v8
	ds_bpermute_b32 v8, v3, v7
	s_nop 0
	v_cvt_pk_bf16_f32 v6, v6, v6
	ds_write_b16 v115, v6 offset:4480
	v_mul_f32_e32 v24, v23, v20
	v_mov_b32_e32 v9, v96
	s_waitcnt lgkmcnt(1)
	v_add_f32_e32 v6, v7, v8
	v_fmamk_f32 v6, v6, 0x3c000000, v187
	v_mul_f32_e32 v7, 0x4b800000, v6
	v_cmp_gt_f32_e32 vcc, s71, v6
	v_mov_b32_e32 v8, v92
	v_mov_b32_e32 v20, v44
	v_cndmask_b32_e32 v6, v6, v7, vcc
	v_rsq_f32_e32 v25, v6
	v_mov_b32_e32 v6, v12
	v_mov_b32_e32 v7, v60
	v_pk_mul_f32 v[6:7], v[6:7], v[132:133] op_sel_hi:[1,0]
	v_mov_b32_e32 v21, v28
	v_pk_fma_f32 v[6:7], v[188:189], v[6:7], v[8:9] neg_lo:[1,0,0] neg_hi:[1,0,0]
	v_pk_mul_f32 v[20:21], v[20:21], v[132:133] op_sel_hi:[1,0]
	v_mov_b32_e32 v22, v84
	v_mov_b32_e32 v23, v88
	v_pk_mul_f32 v[8:9], v[6:7], v[6:7]
	v_pk_fma_f32 v[20:21], v[188:189], v[20:21], v[22:23] neg_lo:[1,0,0] neg_hi:[1,0,0]
	v_add_f32_e32 v8, v8, v9
	v_pk_mul_f32 v[22:23], v[20:21], v[20:21]
	v_mul_f32_e32 v12, v18, v24
	v_add_f32_e32 v8, v8, v22
	v_add_f32_e32 v8, v8, v23
	s_nop 1
	v_mov_b32_dpp v9, v8 quad_perm:[1,0,3,2] row_mask:0xf bank_mask:0xf
	s_nop 0
	v_cvt_pk_bf16_f32 v12, v12, v12
	ds_write_b16 v115, v12 offset:4544
	v_mul_f32_e32 v12, 0x45800000, v25
	v_cndmask_b32_e32 v12, v25, v12, vcc
	s_waitcnt lgkmcnt(1)
; __device__ __forceinline__ u16 f2bf(float f) { return (u16)(cvtpk(f, f) & 0xffffu); }
; __device__ __forceinline__ void phase3(const Params& p, char* shm) {
;     ...
;     for (int r = 0; r < 16; ++r) {
;       float ss = 0.f;
; #pragma unroll
;       for (int d0 = 0; d0 < 4; ++d0) ss += o[d0][r] * o[d0][r];
;       ss += __shfl_xor(ss, 1); ss += __shfl_xor(ss, 2); ss += __shfl_xor(ss, 4); ss += __shfl_xor(ss, 8); ss += __shfl_xor(ss, 16);
;       const float rstd = rsqrtf(ss * (1.f / 128.f) + 1e-6f);
; #pragma unroll
;       for (int d0 = 0; d0 < 4; ++d0) *(u16*)(otb + (((r & 3) + 8 * (r >> 2)) * OT_LD + d0 * 32) * 2) = f2bf(o[d0][r] * rstd * sw[d0]);
;     }
	v_add_f32_e32 v8, v8, v9
	s_nop 1
	v_mov_b32_dpp v9, v8 quad_perm:[2,3,0,1] row_mask:0xf bank_mask:0xf
	v_mul_f32_e32 v4, v4, v12
	v_mul_f32_e32 v4, v51, v4
	s_nop 0
	v_cvt_pk_bf16_f32 v4, v4, v4
	ds_write_b16 v115, v4 offset:4624
	s_waitcnt lgkmcnt(1)
	v_add_f32_e32 v8, v8, v9
	s_nop 1
	v_mov_b32_dpp v9, v8 row_half_mirror row_mask:0xf bank_mask:0xf
	v_mul_f32_e32 v4, v5, v12
	v_mul_f32_e32 v4, v50, v4
	s_nop 0
	v_cvt_pk_bf16_f32 v4, v4, v4
	ds_write_b16 v115, v4 offset:4688
	s_waitcnt lgkmcnt(1)
	v_add_f32_e32 v5, v8, v9
	s_nop 1
	v_mov_b32_dpp v8, v5 row_mirror row_mask:0xf bank_mask:0xf
	v_mul_f32_e32 v4, v10, v12
	v_mul_f32_e32 v4, v19, v4
	s_nop 0
	v_cvt_pk_bf16_f32 v4, v4, v4
	ds_write_b16 v115, v4 offset:4752
	s_waitcnt lgkmcnt(1)
	v_add_f32_e32 v5, v5, v8
	ds_bpermute_b32 v8, v3, v5
	v_mul_f32_e32 v4, v11, v12
	v_mul_f32_e32 v4, v18, v4
	s_nop 0
	v_cvt_pk_bf16_f32 v22, v4, v4
	v_mov_b32_e32 v60, v13
	s_waitcnt lgkmcnt(0)
	v_add_f32_e32 v4, v5, v8
	v_fmamk_f32 v23, v4, 0x3c000000, v187
	v_pk_mul_f32 v[4:5], v[60:61], v[130:131] op_sel_hi:[1,0]
	v_mov_b32_e32 v96, v93
	v_mov_b32_e32 v28, v45
	v_pk_fma_f32 v[4:5], v[188:189], v[4:5], v[96:97] neg_lo:[1,0,0] neg_hi:[1,0,0]
	v_pk_mul_f32 v[10:11], v[28:29], v[130:131] op_sel_hi:[1,0]
	v_mov_b32_e32 v88, v85
	v_pk_mul_f32 v[8:9], v[4:5], v[4:5]
	v_pk_fma_f32 v[10:11], v[188:189], v[10:11], v[88:89] neg_lo:[1,0,0] neg_hi:[1,0,0]
	v_add_f32_e32 v8, v8, v9
	v_pk_mul_f32 v[12:13], v[10:11], v[10:11]
	v_cmp_gt_f32_e32 vcc, s71, v23
	v_add_f32_e32 v8, v8, v12
	v_add_f32_e32 v8, v8, v13
	s_nop 1
	v_mov_b32_dpp v9, v8 quad_perm:[1,0,3,2] row_mask:0xf bank_mask:0xf
	v_mul_f32_e32 v12, 0x4b800000, v23
	v_cndmask_b32_e32 v12, v23, v12, vcc
	v_rsq_f32_e32 v12, v12
	ds_write_b16 v115, v22 offset:4816
	s_waitcnt lgkmcnt(1)
	v_add_f32_e32 v8, v8, v9
	s_nop 1
	v_mov_b32_dpp v9, v8 quad_perm:[2,3,0,1] row_mask:0xf bank_mask:0xf
	v_mul_f32_e32 v13, 0x45800000, v12
	v_cndmask_b32_e32 v12, v12, v13, vcc
	v_mul_f32_e32 v6, v6, v12
	v_mul_f32_e32 v6, v51, v6
	s_waitcnt lgkmcnt(0)
	v_add_f32_e32 v8, v8, v9
	s_nop 1
	v_mov_b32_dpp v9, v8 row_half_mirror row_mask:0xf bank_mask:0xf
	s_nop 0
	v_cvt_pk_bf16_f32 v6, v6, v6
	ds_write_b16 v115, v6 offset:4896
	v_mul_f32_e32 v6, v7, v12
	v_mul_f32_e32 v6, v50, v6
	s_waitcnt lgkmcnt(1)
	v_add_f32_e32 v7, v8, v9
	s_nop 1
	v_mov_b32_dpp v8, v7 row_mirror row_mask:0xf bank_mask:0xf
	s_nop 0
	v_cvt_pk_bf16_f32 v6, v6, v6
	ds_write_b16 v115, v6 offset:4960
	v_mul_f32_e32 v6, v20, v12
	v_mul_f32_e32 v6, v19, v6
	s_waitcnt lgkmcnt(1)
	v_add_f32_e32 v7, v7, v8
	ds_bpermute_b32 v8, v3, v7
	s_nop 0
	v_cvt_pk_bf16_f32 v6, v6, v6
	ds_write_b16 v115, v6 offset:5024
	v_mul_f32_e32 v22, v21, v12
	v_mov_b32_e32 v9, v78
	s_waitcnt lgkmcnt(1)
	v_add_f32_e32 v6, v7, v8
	v_fmamk_f32 v6, v6, 0x3c000000, v187
	v_mul_f32_e32 v7, 0x4b800000, v6
	v_cmp_gt_f32_e32 vcc, s71, v6
	v_mov_b32_e32 v8, v74
	v_mov_b32_e32 v12, v46
	v_cndmask_b32_e32 v6, v6, v7, vcc
	v_rsq_f32_e32 v23, v6
	v_mov_b32_e32 v6, v14
	v_mov_b32_e32 v7, v62
	v_pk_mul_f32 v[6:7], v[6:7], v[118:119] op_sel_hi:[1,0]
	v_mov_b32_e32 v13, v30
	v_pk_fma_f32 v[6:7], v[188:189], v[6:7], v[8:9] neg_lo:[1,0,0] neg_hi:[1,0,0]
	v_pk_mul_f32 v[12:13], v[12:13], v[118:119] op_sel_hi:[1,0]
	v_mov_b32_e32 v20, v66
	v_mov_b32_e32 v21, v70
	v_pk_mul_f32 v[8:9], v[6:7], v[6:7]
	v_pk_fma_f32 v[12:13], v[188:189], v[12:13], v[20:21] neg_lo:[1,0,0] neg_hi:[1,0,0]
	v_add_f32_e32 v8, v8, v9
	v_pk_mul_f32 v[20:21], v[12:13], v[12:13]
	v_mul_f32_e32 v14, v18, v22
	v_add_f32_e32 v8, v8, v20
	v_add_f32_e32 v8, v8, v21
	s_nop 1
	v_mov_b32_dpp v9, v8 quad_perm:[1,0,3,2] row_mask:0xf bank_mask:0xf
	s_nop 0
	v_cvt_pk_bf16_f32 v14, v14, v14
	ds_write_b16 v115, v14 offset:5088
	v_mul_f32_e32 v14, 0x45800000, v23
	v_cndmask_b32_e32 v14, v23, v14, vcc
	s_waitcnt lgkmcnt(1)
	v_add_f32_e32 v8, v8, v9
	s_nop 1
	v_mov_b32_dpp v9, v8 quad_perm:[2,3,0,1] row_mask:0xf bank_mask:0xf
	v_mul_f32_e32 v4, v4, v14
	v_mul_f32_e32 v4, v51, v4
	s_nop 0
	v_cvt_pk_bf16_f32 v4, v4, v4
	ds_write_b16 v115, v4 offset:5168
	s_waitcnt lgkmcnt(1)
	v_add_f32_e32 v8, v8, v9
	s_nop 1
	v_mov_b32_dpp v9, v8 row_half_mirror row_mask:0xf bank_mask:0xf
	v_mul_f32_e32 v4, v5, v14
	v_mul_f32_e32 v4, v50, v4
	s_nop 0
	v_cvt_pk_bf16_f32 v4, v4, v4
	ds_write_b16 v115, v4 offset:5232
	s_waitcnt lgkmcnt(1)
	v_add_f32_e32 v5, v8, v9
	s_nop 1
	v_mov_b32_dpp v8, v5 row_mirror row_mask:0xf bank_mask:0xf
	v_mul_f32_e32 v4, v10, v14
	v_mul_f32_e32 v4, v19, v4
	s_nop 0
	v_cvt_pk_bf16_f32 v4, v4, v4
	ds_write_b16 v115, v4 offset:5296
	s_waitcnt lgkmcnt(1)
	v_add_f32_e32 v5, v5, v8
	ds_bpermute_b32 v8, v3, v5
	v_mul_f32_e32 v4, v11, v14
	v_mul_f32_e32 v4, v18, v4
	s_nop 0
	v_cvt_pk_bf16_f32 v20, v4, v4
	v_mov_b32_e32 v62, v15
	s_waitcnt lgkmcnt(0)
	v_add_f32_e32 v4, v5, v8
	v_fmamk_f32 v21, v4, 0x3c000000, v187
	v_pk_mul_f32 v[4:5], v[62:63], v[114:115] op_sel_hi:[1,0]
	v_mov_b32_e32 v78, v75
	v_mov_b32_e32 v30, v47
	v_pk_fma_f32 v[4:5], v[188:189], v[4:5], v[78:79] neg_lo:[1,0,0] neg_hi:[1,0,0]
	v_pk_mul_f32 v[10:11], v[30:31], v[114:115] op_sel_hi:[1,0]
	v_mov_b32_e32 v70, v67
	v_pk_mul_f32 v[8:9], v[4:5], v[4:5]
	v_pk_fma_f32 v[10:11], v[188:189], v[10:11], v[70:71] neg_lo:[1,0,0] neg_hi:[1,0,0]
	v_add_f32_e32 v8, v8, v9
	v_pk_mul_f32 v[14:15], v[10:11], v[10:11]
	v_cmp_gt_f32_e32 vcc, s71, v21
	v_add_f32_e32 v8, v8, v14
	v_add_f32_e32 v8, v8, v15
	s_nop 1
	v_mov_b32_dpp v9, v8 quad_perm:[1,0,3,2] row_mask:0xf bank_mask:0xf
	v_mul_f32_e32 v14, 0x4b800000, v21
	v_cndmask_b32_e32 v14, v21, v14, vcc
	v_rsq_f32_e32 v14, v14
	ds_write_b16 v115, v20 offset:5360
	s_waitcnt lgkmcnt(1)
; __device__ __forceinline__ u16 f2bf(float f) { return (u16)(cvtpk(f, f) & 0xffffu); }
; __device__ __forceinline__ void phase3(const Params& p, char* shm) {
;     ...
;     for (int r = 0; r < 16; ++r) {
;       float ss = 0.f;
; #pragma unroll
;       for (int d0 = 0; d0 < 4; ++d0) ss += o[d0][r] * o[d0][r];
;       ss += __shfl_xor(ss, 1); ss += __shfl_xor(ss, 2); ss += __shfl_xor(ss, 4); ss += __shfl_xor(ss, 8); ss += __shfl_xor(ss, 16);
;       const float rstd = rsqrtf(ss * (1.f / 128.f) + 1e-6f);
; #pragma unroll
;       for (int d0 = 0; d0 < 4; ++d0) *(u16*)(otb + (((r & 3) + 8 * (r >> 2)) * OT_LD + d0 * 32) * 2) = f2bf(o[d0][r] * rstd * sw[d0]);
;     }
;     __syncthreads();
	v_add_f32_e32 v8, v8, v9
	s_nop 1
	v_mov_b32_dpp v9, v8 quad_perm:[2,3,0,1] row_mask:0xf bank_mask:0xf
	v_mul_f32_e32 v15, 0x45800000, v14
	v_cndmask_b32_e32 v14, v14, v15, vcc
	v_mul_f32_e32 v6, v6, v14
	v_mul_f32_e32 v6, v51, v6
	s_waitcnt lgkmcnt(0)
	v_add_f32_e32 v8, v8, v9
	s_nop 1
	v_mov_b32_dpp v9, v8 row_half_mirror row_mask:0xf bank_mask:0xf
	s_nop 0
	v_cvt_pk_bf16_f32 v6, v6, v6
	ds_write_b16 v115, v6 offset:6528
	v_mul_f32_e32 v6, v7, v14
	v_mul_f32_e32 v6, v50, v6
	s_waitcnt lgkmcnt(1)
	v_add_f32_e32 v7, v8, v9
	s_nop 1
	v_mov_b32_dpp v8, v7 row_mirror row_mask:0xf bank_mask:0xf
	s_nop 0
	v_cvt_pk_bf16_f32 v6, v6, v6
	ds_write_b16 v115, v6 offset:6592
	v_mul_f32_e32 v6, v12, v14
	v_mul_f32_e32 v6, v19, v6
	s_waitcnt lgkmcnt(1)
	v_add_f32_e32 v7, v7, v8
	ds_bpermute_b32 v8, v3, v7
	s_nop 0
	v_cvt_pk_bf16_f32 v6, v6, v6
	ds_write_b16 v115, v6 offset:6656
	v_mul_f32_e32 v20, v13, v14
	v_mov_b32_e32 v9, v80
	s_waitcnt lgkmcnt(1)
	v_add_f32_e32 v6, v7, v8
	v_fmamk_f32 v6, v6, 0x3c000000, v187
	v_mul_f32_e32 v7, 0x4b800000, v6
	v_cmp_gt_f32_e32 vcc, s71, v6
	v_mov_b32_e32 v8, v76
	v_mov_b32_e32 v12, v48
	v_cndmask_b32_e32 v6, v6, v7, vcc
	v_rsq_f32_e32 v21, v6
	v_mov_b32_e32 v6, v16
	v_mov_b32_e32 v7, v64
	v_pk_mul_f32 v[6:7], v[6:7], v[34:35] op_sel_hi:[1,0]
	v_mov_b32_e32 v13, v32
	v_pk_fma_f32 v[6:7], v[188:189], v[6:7], v[8:9] neg_lo:[1,0,0] neg_hi:[1,0,0]
	v_pk_mul_f32 v[12:13], v[12:13], v[34:35] op_sel_hi:[1,0]
	v_mov_b32_e32 v14, v68
	v_mov_b32_e32 v15, v72
	v_pk_mul_f32 v[8:9], v[6:7], v[6:7]
	v_pk_fma_f32 v[12:13], v[188:189], v[12:13], v[14:15] neg_lo:[1,0,0] neg_hi:[1,0,0]
	v_add_f32_e32 v8, v8, v9
	v_pk_mul_f32 v[14:15], v[12:13], v[12:13]
	v_mov_b32_e32 v64, v17
	v_add_f32_e32 v8, v8, v14
	v_add_f32_e32 v8, v8, v15
	s_nop 1
	v_mov_b32_dpp v9, v8 quad_perm:[1,0,3,2] row_mask:0xf bank_mask:0xf
	v_mul_f32_e32 v14, v18, v20
	s_nop 0
	v_cvt_pk_bf16_f32 v14, v14, v14
	ds_write_b16 v115, v14 offset:6720
	v_mul_f32_e32 v14, 0x45800000, v21
	s_waitcnt lgkmcnt(1)
	v_add_f32_e32 v8, v8, v9
	s_nop 1
	v_mov_b32_dpp v9, v8 quad_perm:[2,3,0,1] row_mask:0xf bank_mask:0xf
	v_cndmask_b32_e32 v14, v21, v14, vcc
	v_mul_f32_e32 v4, v4, v14
	v_mul_f32_e32 v4, v51, v4
	s_nop 0
	v_cvt_pk_bf16_f32 v4, v4, v4
	s_waitcnt lgkmcnt(0)
	v_add_f32_e32 v8, v8, v9
	s_nop 1
	v_mov_b32_dpp v9, v8 row_half_mirror row_mask:0xf bank_mask:0xf
	ds_write_b16 v115, v4 offset:6800
	v_mul_f32_e32 v4, v5, v14
	v_mul_f32_e32 v4, v50, v4
	s_nop 0
	v_cvt_pk_bf16_f32 v4, v4, v4
	s_waitcnt lgkmcnt(1)
	v_add_f32_e32 v5, v8, v9
	s_nop 1
	v_mov_b32_dpp v8, v5 row_mirror row_mask:0xf bank_mask:0xf
	ds_write_b16 v115, v4 offset:6864
	v_mul_f32_e32 v4, v10, v14
	v_mul_f32_e32 v4, v19, v4
	s_nop 0
	v_cvt_pk_bf16_f32 v4, v4, v4
	s_waitcnt lgkmcnt(1)
	v_add_f32_e32 v5, v5, v8
	ds_bpermute_b32 v8, v3, v5
	ds_write_b16 v115, v4 offset:6928
	v_mul_f32_e32 v4, v11, v14
	v_mul_f32_e32 v4, v18, v4
	s_nop 0
	v_cvt_pk_bf16_f32 v16, v4, v4
	s_waitcnt lgkmcnt(1)
	v_add_f32_e32 v4, v5, v8
	v_fmamk_f32 v20, v4, 0x3c000000, v187
	v_pk_mul_f32 v[4:5], v[64:65], v[2:3] op_sel_hi:[1,0]
	v_mov_b32_e32 v80, v77
	v_mov_b32_e32 v32, v49
	v_pk_fma_f32 v[4:5], v[188:189], v[4:5], v[80:81] neg_lo:[1,0,0] neg_hi:[1,0,0]
	v_pk_mul_f32 v[10:11], v[32:33], v[2:3] op_sel_hi:[1,0]
	v_mov_b32_e32 v72, v69
	v_pk_mul_f32 v[8:9], v[4:5], v[4:5]
	v_pk_fma_f32 v[10:11], v[188:189], v[10:11], v[72:73] neg_lo:[1,0,0] neg_hi:[1,0,0]
	v_add_f32_e32 v2, v8, v9
	v_pk_mul_f32 v[14:15], v[10:11], v[10:11]
	v_mul_f32_e32 v9, 0x4b800000, v20
	v_add_f32_e32 v2, v2, v14
	v_add_f32_e32 v2, v2, v15
	s_nop 1
	v_mov_b32_dpp v8, v2 quad_perm:[1,0,3,2] row_mask:0xf bank_mask:0xf
	v_cmp_gt_f32_e32 vcc, s71, v20
	ds_write_b16 v115, v16 offset:6992
	s_waitcnt lgkmcnt(1)
	v_add_f32_e32 v2, v2, v8
	s_nop 1
	v_mov_b32_dpp v8, v2 quad_perm:[2,3,0,1] row_mask:0xf bank_mask:0xf
	v_cndmask_b32_e32 v9, v20, v9, vcc
	v_rsq_f32_e32 v9, v9
	s_waitcnt lgkmcnt(0)
	v_add_f32_e32 v2, v2, v8
	s_nop 1
	v_mov_b32_dpp v8, v2 row_half_mirror row_mask:0xf bank_mask:0xf
	v_mul_f32_e32 v14, 0x45800000, v9
	v_cndmask_b32_e32 v9, v9, v14, vcc
	v_mul_f32_e32 v6, v6, v9
	v_mul_f32_e32 v6, v51, v6
	s_nop 0
	v_cvt_pk_bf16_f32 v6, v6, v6
	s_waitcnt lgkmcnt(0)
	v_add_f32_e32 v2, v2, v8
	ds_write_b16 v115, v6 offset:7072
	v_mul_f32_e32 v6, v7, v9
	s_nop 1
	v_mov_b32_dpp v7, v2 row_mirror row_mask:0xf bank_mask:0xf
	v_mul_f32_e32 v6, v50, v6
	s_nop 0
	v_cvt_pk_bf16_f32 v6, v6, v6
	ds_write_b16 v115, v6 offset:7136
	v_mul_f32_e32 v6, v12, v9
	s_waitcnt lgkmcnt(1)
	v_add_f32_e32 v2, v2, v7
	ds_bpermute_b32 v3, v3, v2
	v_mul_f32_e32 v6, v19, v6
	s_nop 0
	v_cvt_pk_bf16_f32 v6, v6, v6
	ds_write_b16 v115, v6 offset:7200
	v_mul_f32_e32 v6, v13, v9
	s_waitcnt lgkmcnt(1)
	v_add_f32_e32 v2, v2, v3
	v_fmamk_f32 v2, v2, 0x3c000000, v187
	v_mul_f32_e32 v3, 0x4b800000, v2
	v_cmp_gt_f32_e32 vcc, s71, v2
	s_nop 1
	v_cndmask_b32_e32 v2, v2, v3, vcc
	v_rsq_f32_e32 v2, v2
	v_mul_f32_e32 v3, v18, v6
	s_nop 0
	v_cvt_pk_bf16_f32 v3, v3, v3
	ds_write_b16 v115, v3 offset:7264
	v_mul_f32_e32 v3, 0x45800000, v2
	v_cndmask_b32_e32 v2, v2, v3, vcc
	v_mul_f32_e32 v3, v4, v2
	v_mul_f32_e32 v3, v51, v3
	s_nop 0
	v_cvt_pk_bf16_f32 v3, v3, v3
	ds_write_b16 v115, v3 offset:7344
	v_mul_f32_e32 v3, v5, v2
	v_mul_f32_e32 v3, v50, v3
	s_nop 0
	v_cvt_pk_bf16_f32 v3, v3, v3
	ds_write_b16 v115, v3 offset:7408
	v_mul_f32_e32 v3, v10, v2
	v_mul_f32_e32 v2, v11, v2
	v_mul_f32_e32 v3, v19, v3
	v_mul_f32_e32 v2, v18, v2
	v_cmp_gt_i32_e32 vcc, s72, v131
	s_nop 0
	v_cvt_pk_bf16_f32 v3, v3, v3
	ds_write_b16 v115, v3 offset:7472
	s_nop 0
	v_cvt_pk_bf16_f32 v2, v2, v2
	ds_write_b16 v115, v2 offset:7536
	s_waitcnt lgkmcnt(0)
	s_barrier
; __device__ __forceinline__ float bflo(unsigned v) { return __uint_as_float(v << 16); }
; __device__ __forceinline__ float bfhi(unsigned v) { return __uint_as_float(v & 0xffff0000u); }
; __device__ __forceinline__ void phase3(const Params& p, char* shm) {
;     ...
;     { const u16* zsrc = Zb + t0 * AW + h * 128; u16* bdst = Bin + t0 * AW + h * 128;
; #pragma unroll 2
;       for (int id = tid; id < 256 * 16; id += NTHR) {
;         const int row = id >> 4, c = id & 15;
;         const u32x4 ov = *reinterpret_cast<const u32x4*>(shm + (row * OT_LD + c * 8) * 2);
;         const u32x4 zv = *reinterpret_cast<const u32x4*>(zsrc + (size_t)row * AW + c * 8);
;         u32x4 w;
; #pragma unroll
;         for (int q = 0; q < 4; ++q) w[q] = cvtpk(bflo(ov[q]) * bflo(zv[q]), bfhi(ov[q]) * bfhi(zv[q]));
;         *reinterpret_cast<u32x4*>(bdst + (size_t)row * AW + c * 8) = w;
;       }
;     }
	s_and_saveexec_b64 s[0:1], vcc
	s_cbranch_execz .LBB0_322
	s_add_u32 s4, s79, s18
	s_addc_u32 s5, s80, s19
	s_add_u32 s4, s4, s86
	s_addc_u32 s5, s5, 0
	s_add_u32 s6, s81, s18
	s_addc_u32 s7, s82, s19
	s_add_u32 s6, s6, s86
	s_addc_u32 s7, s7, 0
	v_lshlrev_b32_e32 v2, 3, v131
	v_lshrrev_b32_e32 v52, 4, v131
	v_and_b32_e32 v53, 15, v131
	v_lshlrev_b32_e32 v54, 11, v52
	v_lshl_add_u32 v54, v53, 4, v54
	v_mul_u32_u24_e32 v52, 0x110, v52
	v_lshl_add_u32 v52, v53, 4, v52
	v_add_u32_e32 v55, 0x10000, v54
	v_add_u32_e32 v56, 0x20000, v54
	v_add_u32_e32 v57, 0x30000, v54
	v_add_u32_e32 v58, 0x40000, v54
	v_add_u32_e32 v59, 0x50000, v54
	v_add_u32_e32 v60, 0x60000, v54
	v_add_u32_e32 v61, 0x70000, v54
	global_load_dwordx4 v[4:7], v54, s[4:5]
	global_load_dwordx4 v[8:11], v55, s[4:5]
	global_load_dwordx4 v[12:15], v56, s[4:5]
	global_load_dwordx4 v[16:19], v57, s[4:5]
	global_load_dwordx4 v[20:23], v58, s[4:5]
	global_load_dwordx4 v[24:27], v59, s[4:5]
	global_load_dwordx4 v[28:31], v60, s[4:5]
	global_load_dwordx4 v[32:35], v61, s[4:5]
	ds_read_b128 v[36:39], v52
	ds_read_b128 v[40:43], v52 offset:8704
	ds_read_b128 v[44:47], v52 offset:17408
	ds_read_b128 v[48:51], v52 offset:26112
	s_waitcnt vmcnt(7) lgkmcnt(3)
	v_lshlrev_b32_e32 v62, 16, v36
	v_lshlrev_b32_e32 v63, 16, v4
	v_and_b32_e32 v36, 0xffff0000, v36
	v_and_b32_e32 v4, 0xffff0000, v4
	v_mul_f32_e32 v62, v63, v62
	v_mul_f32_e32 v4, v4, v36
	v_cvt_pk_bf16_f32 v4, v62, v4
	v_lshlrev_b32_e32 v62, 16, v37
	v_lshlrev_b32_e32 v63, 16, v5
	v_and_b32_e32 v37, 0xffff0000, v37
	v_and_b32_e32 v5, 0xffff0000, v5
	v_mul_f32_e32 v62, v63, v62
	v_mul_f32_e32 v5, v5, v37
	v_cvt_pk_bf16_f32 v5, v62, v5
	v_lshlrev_b32_e32 v62, 16, v38
	v_lshlrev_b32_e32 v63, 16, v6
	v_and_b32_e32 v38, 0xffff0000, v38
	v_and_b32_e32 v6, 0xffff0000, v6
	v_mul_f32_e32 v62, v63, v62
	v_mul_f32_e32 v6, v6, v38
	v_cvt_pk_bf16_f32 v6, v62, v6
	v_lshlrev_b32_e32 v62, 16, v39
	v_lshlrev_b32_e32 v63, 16, v7
	v_and_b32_e32 v39, 0xffff0000, v39
	v_and_b32_e32 v7, 0xffff0000, v7
	v_mul_f32_e32 v62, v63, v62
	v_mul_f32_e32 v7, v7, v39
	v_cvt_pk_bf16_f32 v7, v62, v7
	global_store_dwordx4 v54, v[4:7], s[6:7]
	s_waitcnt vmcnt(7) lgkmcnt(2)
	v_lshlrev_b32_e32 v62, 16, v40
	v_lshlrev_b32_e32 v63, 16, v8
	v_and_b32_e32 v40, 0xffff0000, v40
	v_and_b32_e32 v8, 0xffff0000, v8
	v_mul_f32_e32 v62, v63, v62
	v_mul_f32_e32 v8, v8, v40
	v_cvt_pk_bf16_f32 v8, v62, v8
	v_lshlrev_b32_e32 v62, 16, v41
	v_lshlrev_b32_e32 v63, 16, v9
	v_and_b32_e32 v41, 0xffff0000, v41
	v_and_b32_e32 v9, 0xffff0000, v9
	v_mul_f32_e32 v62, v63, v62
	v_mul_f32_e32 v9, v9, v41
	v_cvt_pk_bf16_f32 v9, v62, v9
	v_lshlrev_b32_e32 v62, 16, v42
	v_lshlrev_b32_e32 v63, 16, v10
	v_and_b32_e32 v42, 0xffff0000, v42
	v_and_b32_e32 v10, 0xffff0000, v10
	v_mul_f32_e32 v62, v63, v62
	v_mul_f32_e32 v10, v10, v42
	v_cvt_pk_bf16_f32 v10, v62, v10
	v_lshlrev_b32_e32 v62, 16, v43
	v_lshlrev_b32_e32 v63, 16, v11
	v_and_b32_e32 v43, 0xffff0000, v43
	v_and_b32_e32 v11, 0xffff0000, v11
	v_mul_f32_e32 v62, v63, v62
	v_mul_f32_e32 v11, v11, v43
	v_cvt_pk_bf16_f32 v11, v62, v11
	global_store_dwordx4 v55, v[8:11], s[6:7]
	s_waitcnt vmcnt(7) lgkmcnt(1)
	v_lshlrev_b32_e32 v62, 16, v44
	v_lshlrev_b32_e32 v63, 16, v12
	v_and_b32_e32 v44, 0xffff0000, v44
	v_and_b32_e32 v12, 0xffff0000, v12
	v_mul_f32_e32 v62, v63, v62
	v_mul_f32_e32 v12, v12, v44
	v_cvt_pk_bf16_f32 v12, v62, v12
	v_lshlrev_b32_e32 v62, 16, v45
	v_lshlrev_b32_e32 v63, 16, v13
	v_and_b32_e32 v45, 0xffff0000, v45
	v_and_b32_e32 v13, 0xffff0000, v13
	v_mul_f32_e32 v62, v63, v62
	v_mul_f32_e32 v13, v13, v45
	v_cvt_pk_bf16_f32 v13, v62, v13
	v_lshlrev_b32_e32 v62, 16, v46
	v_lshlrev_b32_e32 v63, 16, v14
	v_and_b32_e32 v46, 0xffff0000, v46
	v_and_b32_e32 v14, 0xffff0000, v14
	v_mul_f32_e32 v62, v63, v62
	v_mul_f32_e32 v14, v14, v46
	v_cvt_pk_bf16_f32 v14, v62, v14
	v_lshlrev_b32_e32 v62, 16, v47
	v_lshlrev_b32_e32 v63, 16, v15
	v_and_b32_e32 v47, 0xffff0000, v47
	v_and_b32_e32 v15, 0xffff0000, v15
	v_mul_f32_e32 v62, v63, v62
	v_mul_f32_e32 v15, v15, v47
	v_cvt_pk_bf16_f32 v15, v62, v15
	global_store_dwordx4 v56, v[12:15], s[6:7]
	s_waitcnt vmcnt(7) lgkmcnt(0)
; __device__ __forceinline__ float bflo(unsigned v) { return __uint_as_float(v << 16); }
; __device__ __forceinline__ float bfhi(unsigned v) { return __uint_as_float(v & 0xffff0000u); }
; __device__ __forceinline__ void phase3(const Params& p, char* shm) {
;     ...
;     { const u16* zsrc = Zb + t0 * AW + h * 128; u16* bdst = Bin + t0 * AW + h * 128;
; #pragma unroll 2
;       for (int id = tid; id < 256 * 16; id += NTHR) {
;         const int row = id >> 4, c = id & 15;
;         const u32x4 ov = *reinterpret_cast<const u32x4*>(shm + (row * OT_LD + c * 8) * 2);
;         const u32x4 zv = *reinterpret_cast<const u32x4*>(zsrc + (size_t)row * AW + c * 8);
;         u32x4 w;
; #pragma unroll
;         for (int q = 0; q < 4; ++q) w[q] = cvtpk(bflo(ov[q]) * bflo(zv[q]), bfhi(ov[q]) * bfhi(zv[q]));
;         *reinterpret_cast<u32x4*>(bdst + (size_t)row * AW + c * 8) = w;
;       }
;     }
	v_lshlrev_b32_e32 v62, 16, v48
	v_lshlrev_b32_e32 v63, 16, v16
	v_and_b32_e32 v48, 0xffff0000, v48
	v_and_b32_e32 v16, 0xffff0000, v16
	v_mul_f32_e32 v62, v63, v62
	v_mul_f32_e32 v16, v16, v48
	v_cvt_pk_bf16_f32 v16, v62, v16
	v_lshlrev_b32_e32 v62, 16, v49
	v_lshlrev_b32_e32 v63, 16, v17
	v_and_b32_e32 v49, 0xffff0000, v49
	v_and_b32_e32 v17, 0xffff0000, v17
	v_mul_f32_e32 v62, v63, v62
	v_mul_f32_e32 v17, v17, v49
	v_cvt_pk_bf16_f32 v17, v62, v17
	v_lshlrev_b32_e32 v62, 16, v50
	v_lshlrev_b32_e32 v63, 16, v18
	v_and_b32_e32 v50, 0xffff0000, v50
	v_and_b32_e32 v18, 0xffff0000, v18
	v_mul_f32_e32 v62, v63, v62
	v_mul_f32_e32 v18, v18, v50
	v_cvt_pk_bf16_f32 v18, v62, v18
	v_lshlrev_b32_e32 v62, 16, v51
	v_lshlrev_b32_e32 v63, 16, v19
	v_and_b32_e32 v51, 0xffff0000, v51
	v_and_b32_e32 v19, 0xffff0000, v19
	v_mul_f32_e32 v62, v63, v62
	v_mul_f32_e32 v19, v19, v51
	v_cvt_pk_bf16_f32 v19, v62, v19
	global_store_dwordx4 v57, v[16:19], s[6:7]
	ds_read_b128 v[36:39], v52 offset:34816
	ds_read_b128 v[40:43], v52 offset:43520
	ds_read_b128 v[44:47], v52 offset:52224
	ds_read_b128 v[48:51], v52 offset:60928
	s_waitcnt vmcnt(7) lgkmcnt(3)
	v_lshlrev_b32_e32 v62, 16, v36
	v_lshlrev_b32_e32 v63, 16, v20
	v_and_b32_e32 v36, 0xffff0000, v36
	v_and_b32_e32 v20, 0xffff0000, v20
	v_mul_f32_e32 v62, v63, v62
	v_mul_f32_e32 v20, v20, v36
	v_cvt_pk_bf16_f32 v20, v62, v20
	v_lshlrev_b32_e32 v62, 16, v37
	v_lshlrev_b32_e32 v63, 16, v21
	v_and_b32_e32 v37, 0xffff0000, v37
	v_and_b32_e32 v21, 0xffff0000, v21
	v_mul_f32_e32 v62, v63, v62
	v_mul_f32_e32 v21, v21, v37
	v_cvt_pk_bf16_f32 v21, v62, v21
	v_lshlrev_b32_e32 v62, 16, v38
	v_lshlrev_b32_e32 v63, 16, v22
	v_and_b32_e32 v38, 0xffff0000, v38
	v_and_b32_e32 v22, 0xffff0000, v22
	v_mul_f32_e32 v62, v63, v62
	v_mul_f32_e32 v22, v22, v38
	v_cvt_pk_bf16_f32 v22, v62, v22
	v_lshlrev_b32_e32 v62, 16, v39
	v_lshlrev_b32_e32 v63, 16, v23
	v_and_b32_e32 v39, 0xffff0000, v39
	v_and_b32_e32 v23, 0xffff0000, v23
	v_mul_f32_e32 v62, v63, v62
	v_mul_f32_e32 v23, v23, v39
	v_cvt_pk_bf16_f32 v23, v62, v23
	global_store_dwordx4 v58, v[20:23], s[6:7]
	s_waitcnt vmcnt(7) lgkmcnt(2)
	v_lshlrev_b32_e32 v62, 16, v40
	v_lshlrev_b32_e32 v63, 16, v24
	v_and_b32_e32 v40, 0xffff0000, v40
	v_and_b32_e32 v24, 0xffff0000, v24
	v_mul_f32_e32 v62, v63, v62
	v_mul_f32_e32 v24, v24, v40
	v_cvt_pk_bf16_f32 v24, v62, v24
	v_lshlrev_b32_e32 v62, 16, v41
	v_lshlrev_b32_e32 v63, 16, v25
	v_and_b32_e32 v41, 0xffff0000, v41
	v_and_b32_e32 v25, 0xffff0000, v25
	v_mul_f32_e32 v62, v63, v62
	v_mul_f32_e32 v25, v25, v41
	v_cvt_pk_bf16_f32 v25, v62, v25
	v_lshlrev_b32_e32 v62, 16, v42
	v_lshlrev_b32_e32 v63, 16, v26
	v_and_b32_e32 v42, 0xffff0000, v42
	v_and_b32_e32 v26, 0xffff0000, v26
	v_mul_f32_e32 v62, v63, v62
	v_mul_f32_e32 v26, v26, v42
	v_cvt_pk_bf16_f32 v26, v62, v26
	v_lshlrev_b32_e32 v62, 16, v43
	v_lshlrev_b32_e32 v63, 16, v27
	v_and_b32_e32 v43, 0xffff0000, v43
	v_and_b32_e32 v27, 0xffff0000, v27
	v_mul_f32_e32 v62, v63, v62
	v_mul_f32_e32 v27, v27, v43
	v_cvt_pk_bf16_f32 v27, v62, v27
	global_store_dwordx4 v59, v[24:27], s[6:7]
	s_waitcnt vmcnt(7) lgkmcnt(1)
	v_lshlrev_b32_e32 v62, 16, v44
	v_lshlrev_b32_e32 v63, 16, v28
	v_and_b32_e32 v44, 0xffff0000, v44
	v_and_b32_e32 v28, 0xffff0000, v28
	v_mul_f32_e32 v62, v63, v62
	v_mul_f32_e32 v28, v28, v44
	v_cvt_pk_bf16_f32 v28, v62, v28
	v_lshlrev_b32_e32 v62, 16, v45
	v_lshlrev_b32_e32 v63, 16, v29
	v_and_b32_e32 v45, 0xffff0000, v45
	v_and_b32_e32 v29, 0xffff0000, v29
	v_mul_f32_e32 v62, v63, v62
	v_mul_f32_e32 v29, v29, v45
	v_cvt_pk_bf16_f32 v29, v62, v29
	v_lshlrev_b32_e32 v62, 16, v46
	v_lshlrev_b32_e32 v63, 16, v30
	v_and_b32_e32 v46, 0xffff0000, v46
	v_and_b32_e32 v30, 0xffff0000, v30
	v_mul_f32_e32 v62, v63, v62
	v_mul_f32_e32 v30, v30, v46
	v_cvt_pk_bf16_f32 v30, v62, v30
	v_lshlrev_b32_e32 v62, 16, v47
	v_lshlrev_b32_e32 v63, 16, v31
	v_and_b32_e32 v47, 0xffff0000, v47
	v_and_b32_e32 v31, 0xffff0000, v31
	v_mul_f32_e32 v62, v63, v62
	v_mul_f32_e32 v31, v31, v47
	v_cvt_pk_bf16_f32 v31, v62, v31
	global_store_dwordx4 v60, v[28:31], s[6:7]
	s_waitcnt vmcnt(7) lgkmcnt(0)
	v_lshlrev_b32_e32 v62, 16, v48
	v_lshlrev_b32_e32 v63, 16, v32
	v_and_b32_e32 v48, 0xffff0000, v48
	v_and_b32_e32 v32, 0xffff0000, v32
	v_mul_f32_e32 v62, v63, v62
	v_mul_f32_e32 v32, v32, v48
	v_cvt_pk_bf16_f32 v32, v62, v32
	v_lshlrev_b32_e32 v62, 16, v49
	v_lshlrev_b32_e32 v63, 16, v33
	v_and_b32_e32 v49, 0xffff0000, v49
	v_and_b32_e32 v33, 0xffff0000, v33
	v_mul_f32_e32 v62, v63, v62
	v_mul_f32_e32 v33, v33, v49
	v_cvt_pk_bf16_f32 v33, v62, v33
	v_lshlrev_b32_e32 v62, 16, v50
	v_lshlrev_b32_e32 v63, 16, v34
	v_and_b32_e32 v50, 0xffff0000, v50
	v_and_b32_e32 v34, 0xffff0000, v34
	v_mul_f32_e32 v62, v63, v62
	v_mul_f32_e32 v34, v34, v50
	v_cvt_pk_bf16_f32 v34, v62, v34
	v_lshlrev_b32_e32 v62, 16, v51
	v_lshlrev_b32_e32 v63, 16, v35
	v_and_b32_e32 v51, 0xffff0000, v51
	v_and_b32_e32 v35, 0xffff0000, v35
	v_mul_f32_e32 v62, v63, v62
	v_mul_f32_e32 v35, v35, v51
	v_cvt_pk_bf16_f32 v35, v62, v35
	global_store_dwordx4 v61, v[32:35], s[6:7]
	v_add_u32_e32 v131, 0x1000, v131
	v_and_b32_e32 v190, 0x78, v2
	v_lshlrev_b32_e32 v190, 1, v190
	v_add_u32_e32 v2, 0x8000, v2
	s_mov_b64 s[18:19], exec
	s_nop 1
	s_branch .LBB0_322
